# v60 + dead LDS staging write of the decay vector removed from the helper loop (scan waves load it from global since v50)
# speedup vs baseline: 1.0043x; 1.0026x over previous
.LBB0_730:
	v_ashrrev_i32_e32 v107, 31, v106
	v_lshlrev_b64 v[98:99], 11, v[106:107]
	v_lshl_add_u64 v[98:99], v[98:99], 0, v[120:121]
	v_lshlrev_b64 v[100:101], 1, v[98:99]
	v_lshl_add_u64 v[102:103], s[12:13], 0, v[100:101]
	v_lshl_add_u64 v[104:105], s[18:19], 0, v[100:101]
	v_lshl_add_u64 v[100:101], s[94:95], 0, v[100:101]
	v_lshlrev_b64 v[98:99], 2, v[98:99]
	v_lshlrev_b64 v[106:107], 12, v[106:107]
	global_load_dwordx2 v[160:161], v[102:103], off
	global_load_dwordx2 v[162:163], v[104:105], off
	global_load_dwordx2 v[158:159], v[100:101], off
	v_lshl_add_u64 v[100:101], s[28:29], 0, v[98:99]
	v_lshl_add_u64 v[98:99], s[30:31], 0, v[98:99]
	v_lshl_add_u64 v[106:107], v[130:131], 0, v[106:107]
	global_load_dwordx4 v[102:105], v[100:101], off
	global_load_dwordx2 v[156:157], v[106:107], off
	s_waitcnt vmcnt(18)
	v_pk_add_f32 v[110:111], v[12:13], -1.0 op_sel_hi:[1,0]
	global_load_dwordx4 v[98:101], v[98:99], off
	v_pk_add_f32 v[112:113], v[10:11], -1.0 op_sel_hi:[1,0]
	v_lshlrev_b32_e32 v188, 16, v142
	v_and_b32_e32 v189, 0xffff0000, v142
	v_lshlrev_b32_e32 v190, 16, v143
	v_and_b32_e32 v191, 0xffff0000, v143
	v_lshlrev_b32_e32 v106, 16, v140
	v_and_b32_e32 v107, 0xffff0000, v140
	v_lshlrev_b32_e32 v108, 16, v141
	v_and_b32_e32 v109, 0xffff0000, v141
	v_pk_fma_f32 v[110:111], v[8:9], v[110:111], 1.0 op_sel_hi:[1,1,0]
	v_pk_fma_f32 v[112:113], v[6:7], v[112:113], 1.0 op_sel_hi:[1,1,0]
	v_pk_mul_f32 v[108:109], v[110:111], v[108:109]
	v_pk_mul_f32 v[106:107], v[112:113], v[106:107]
	v_lshlrev_b32_e32 v110, 16, v134
	v_and_b32_e32 v111, 0xffff0000, v134
	v_lshlrev_b32_e32 v112, 16, v135
	v_and_b32_e32 v113, 0xffff0000, v135
	v_xor_b32_e32 v143, 0x80000000, v191
	v_xor_b32_e32 v142, 0x80000000, v190
	v_xor_b32_e32 v141, 0x80000000, v189
	v_xor_b32_e32 v140, 0x80000000, v188
	v_pk_mul_f32 v[12:13], v[12:13], v[190:191]
	v_pk_mul_f32 v[10:11], v[10:11], v[188:189]
	ds_write_b128 v124, v[140:143] offset:20480
	ds_write_b128 v124, v[10:13] offset:20992
	ds_write_b128 v124, v[106:109] offset:21248
	ds_write_b128 v124, v[110:113] offset:21504
	s_and_saveexec_b64 s[40:41], s[6:7]
	s_cbranch_execz .LBB0_732
	s_waitcnt vmcnt(18)
	v_lshlrev_b32_e32 v10, 16, v136
	v_and_b32_e32 v11, 0xffff0000, v136
	v_lshlrev_b32_e32 v12, 16, v137
	v_and_b32_e32 v13, 0xffff0000, v137
	ds_write_b128 v186, v[10:13] offset:43008

.LBB0_756:
	v_ashrrev_i32_e32 v107, 31, v106
	v_lshlrev_b64 v[10:11], 11, v[106:107]
	v_lshl_add_u64 v[10:11], v[10:11], 0, v[120:121]
	v_lshlrev_b64 v[12:13], 1, v[10:11]
	v_lshl_add_u64 v[14:15], s[12:13], 0, v[12:13]
	v_lshl_add_u64 v[16:17], s[18:19], 0, v[12:13]
	v_lshl_add_u64 v[12:13], s[94:95], 0, v[12:13]
	v_lshlrev_b64 v[10:11], 2, v[10:11]
	v_lshlrev_b64 v[106:107], 12, v[106:107]
	global_load_dwordx2 v[140:141], v[14:15], off
	global_load_dwordx2 v[142:143], v[16:17], off
	global_load_dwordx2 v[134:135], v[12:13], off
	v_lshl_add_u64 v[12:13], s[28:29], 0, v[10:11]
	v_lshl_add_u64 v[10:11], s[30:31], 0, v[10:11]
	v_lshl_add_u64 v[106:107], v[130:131], 0, v[106:107]
	global_load_dwordx4 v[14:17], v[12:13], off
	global_load_dwordx2 v[136:137], v[106:107], off
	s_waitcnt vmcnt(19)
	v_pk_add_f32 v[110:111], v[20:21], -1.0 op_sel_hi:[1,0]
	global_load_dwordx4 v[10:13], v[10:11], off
	v_pk_add_f32 v[112:113], v[18:19], -1.0 op_sel_hi:[1,0]
	v_lshlrev_b32_e32 v188, 16, v146
	v_and_b32_e32 v189, 0xffff0000, v146
	v_lshlrev_b32_e32 v190, 16, v147
	v_and_b32_e32 v191, 0xffff0000, v147
	v_lshlrev_b32_e32 v106, 16, v144
	v_and_b32_e32 v107, 0xffff0000, v144
	v_lshlrev_b32_e32 v108, 16, v145
	v_and_b32_e32 v109, 0xffff0000, v145
	v_pk_fma_f32 v[110:111], v[8:9], v[110:111], 1.0 op_sel_hi:[1,1,0]
	v_pk_fma_f32 v[112:113], v[6:7], v[112:113], 1.0 op_sel_hi:[1,1,0]
	v_pk_mul_f32 v[108:109], v[110:111], v[108:109]
	v_pk_mul_f32 v[106:107], v[112:113], v[106:107]
	v_lshlrev_b32_e32 v110, 16, v138
	v_and_b32_e32 v111, 0xffff0000, v138
	v_lshlrev_b32_e32 v112, 16, v139
	v_and_b32_e32 v113, 0xffff0000, v139
	v_xor_b32_e32 v147, 0x80000000, v191
	v_xor_b32_e32 v146, 0x80000000, v190
	v_xor_b32_e32 v145, 0x80000000, v189
	v_xor_b32_e32 v144, 0x80000000, v188
	v_pk_mul_f32 v[20:21], v[20:21], v[190:191]
	v_pk_mul_f32 v[18:19], v[18:19], v[188:189]
	ds_write_b128 v124, v[144:147]
	ds_write_b128 v124, v[18:21] offset:512
	ds_write_b128 v124, v[106:109] offset:768
	ds_write_b128 v124, v[110:113] offset:1024
	s_and_saveexec_b64 s[40:41], s[6:7]
	v_lshlrev_b32_e32 v18, 16, v132
	v_and_b32_e32 v19, 0xffff0000, v132
	v_lshlrev_b32_e32 v20, 16, v133
	v_and_b32_e32 v21, 0xffff0000, v133
	ds_write_b128 v186, v[18:21] offset:40960
	s_or_b64 exec, exec, s[40:41]
	v_pk_mul_f32 v[18:19], v[108:109], v[112:113]
	v_pk_mul_f32 v[20:21], v[106:107], v[110:111]
	v_mul_f32_e32 v19, v5, v19
	v_mul_f32_e32 v21, v3, v21
	v_fmac_f32_e32 v21, v2, v20
	v_fmac_f32_e32 v19, v4, v18
	v_add_f32_e32 v18, v21, v19
	v_mov_b32_e32 v20, 0
	s_nop 0
	v_add_f32_dpp v18, v18, v18 row_ror:8 row_mask:0xf bank_mask:0xf bound_ctrl:1
	s_nop 1
	v_add_f32_dpp v18, v18, v18 row_ror:4 row_mask:0xf bank_mask:0xf bound_ctrl:1
	s_nop 1
	v_add_f32_dpp v19, v18, v18 row_ror:2 row_mask:0xf bank_mask:0xf bound_ctrl:1
	s_nop 1
	v_mov_b32_dpp v20, v19 row_ror:1 row_mask:0xf bank_mask:0xf
	s_and_saveexec_b64 s[40:41], s[8:9]
	s_cbranch_execz .LBB0_764
	s_and_b64 vcc, exec, s[4:5]
	s_mov_b64 s[52:53], -1
	s_cbranch_vccnz .LBB0_761
	v_lshl_add_u32 v18, s46, 4, v167
	v_sub_u32_e32 v18, 0x1fdf, v18
	s_mov_b64 s[52:53], 0

.LBB0_782:
	v_ashrrev_i32_e32 v107, 31, v106
	v_lshlrev_b64 v[18:19], 11, v[106:107]
	v_lshl_add_u64 v[18:19], v[18:19], 0, v[120:121]
	v_lshlrev_b64 v[20:21], 1, v[18:19]
	v_lshl_add_u64 v[22:23], s[12:13], 0, v[20:21]
	v_lshl_add_u64 v[24:25], s[18:19], 0, v[20:21]
	v_lshl_add_u64 v[20:21], s[94:95], 0, v[20:21]
	v_lshlrev_b64 v[18:19], 2, v[18:19]
	v_lshlrev_b64 v[106:107], 12, v[106:107]
	global_load_dwordx2 v[144:145], v[22:23], off
	global_load_dwordx2 v[146:147], v[24:25], off
	global_load_dwordx2 v[138:139], v[20:21], off
	v_lshl_add_u64 v[20:21], s[28:29], 0, v[18:19]
	v_lshl_add_u64 v[18:19], s[30:31], 0, v[18:19]
	v_lshl_add_u64 v[106:107], v[130:131], 0, v[106:107]
	global_load_dwordx4 v[22:25], v[20:21], off
	global_load_dwordx2 v[132:133], v[106:107], off
	s_waitcnt vmcnt(22)
	v_pk_add_f32 v[110:111], v[92:93], -1.0 op_sel_hi:[1,0]
	global_load_dwordx4 v[18:21], v[18:19], off
	v_pk_add_f32 v[112:113], v[90:91], -1.0 op_sel_hi:[1,0]
	v_lshlrev_b32_e32 v190, 16, v154
	v_and_b32_e32 v191, 0xffff0000, v154
	v_lshlrev_b32_e32 v154, 16, v155
	v_and_b32_e32 v155, 0xffff0000, v155
	v_lshlrev_b32_e32 v106, 16, v152
	v_and_b32_e32 v107, 0xffff0000, v152
	v_lshlrev_b32_e32 v108, 16, v153
	v_and_b32_e32 v109, 0xffff0000, v153
	v_pk_fma_f32 v[110:111], v[8:9], v[110:111], 1.0 op_sel_hi:[1,1,0]
	v_pk_fma_f32 v[112:113], v[6:7], v[112:113], 1.0 op_sel_hi:[1,1,0]
	v_pk_mul_f32 v[108:109], v[110:111], v[108:109]
	v_pk_mul_f32 v[106:107], v[112:113], v[106:107]
	v_lshlrev_b32_e32 v110, 16, v150
	v_and_b32_e32 v111, 0xffff0000, v150
	v_lshlrev_b32_e32 v112, 16, v151
	v_and_b32_e32 v113, 0xffff0000, v151
	v_xor_b32_e32 v153, 0x80000000, v155
	v_xor_b32_e32 v152, 0x80000000, v154
	v_xor_b32_e32 v151, 0x80000000, v191
	v_xor_b32_e32 v150, 0x80000000, v190
	v_pk_mul_f32 v[92:93], v[92:93], v[154:155]
	v_pk_mul_f32 v[90:91], v[90:91], v[190:191]
	ds_write_b128 v124, v[150:153] offset:20480
	ds_write_b128 v124, v[90:93] offset:20992
	ds_write_b128 v124, v[106:109] offset:21248
	ds_write_b128 v124, v[110:113] offset:21504
	s_and_saveexec_b64 s[52:53], s[6:7]
	s_cbranch_execz .LBB0_784
	s_waitcnt vmcnt(22)
	v_lshlrev_b32_e32 v90, 16, v148
	v_and_b32_e32 v91, 0xffff0000, v148
	v_lshlrev_b32_e32 v92, 16, v149
	v_and_b32_e32 v93, 0xffff0000, v149
	ds_write_b128 v186, v[90:93] offset:43008

.LBB0_809:
	v_ashrrev_i32_e32 v107, 31, v106
	v_lshlrev_b64 v[90:91], 11, v[106:107]
	v_lshl_add_u64 v[90:91], v[90:91], 0, v[120:121]
	v_lshlrev_b64 v[92:93], 1, v[90:91]
	v_lshl_add_u64 v[94:95], s[12:13], 0, v[92:93]
	v_lshl_add_u64 v[96:97], s[18:19], 0, v[92:93]
	v_lshl_add_u64 v[92:93], s[94:95], 0, v[92:93]
	v_lshlrev_b64 v[90:91], 2, v[90:91]
	v_lshlrev_b64 v[106:107], 12, v[106:107]
	global_load_dwordx2 v[152:153], v[94:95], off
	global_load_dwordx2 v[154:155], v[96:97], off
	global_load_dwordx2 v[150:151], v[92:93], off
	v_lshl_add_u64 v[92:93], s[28:29], 0, v[90:91]
	v_lshl_add_u64 v[90:91], s[30:31], 0, v[90:91]
	v_lshl_add_u64 v[106:107], v[130:131], 0, v[106:107]
	global_load_dwordx4 v[94:97], v[92:93], off
	global_load_dwordx2 v[148:149], v[106:107], off
	s_waitcnt vmcnt(23)
	v_pk_add_f32 v[110:111], v[100:101], -1.0 op_sel_hi:[1,0]
	global_load_dwordx4 v[90:93], v[90:91], off
	v_pk_add_f32 v[112:113], v[98:99], -1.0 op_sel_hi:[1,0]
	v_lshlrev_b32_e32 v190, 16, v162
	v_and_b32_e32 v191, 0xffff0000, v162
	v_lshlrev_b32_e32 v162, 16, v163
	v_and_b32_e32 v163, 0xffff0000, v163
	v_lshlrev_b32_e32 v106, 16, v160
	v_and_b32_e32 v107, 0xffff0000, v160
	v_lshlrev_b32_e32 v108, 16, v161
	v_and_b32_e32 v109, 0xffff0000, v161
	v_pk_fma_f32 v[110:111], v[8:9], v[110:111], 1.0 op_sel_hi:[1,1,0]
	v_pk_fma_f32 v[112:113], v[6:7], v[112:113], 1.0 op_sel_hi:[1,1,0]
	v_pk_mul_f32 v[108:109], v[110:111], v[108:109]
	v_pk_mul_f32 v[106:107], v[112:113], v[106:107]
	v_lshlrev_b32_e32 v110, 16, v158
	v_and_b32_e32 v111, 0xffff0000, v158
	v_lshlrev_b32_e32 v112, 16, v159
	v_and_b32_e32 v113, 0xffff0000, v159
	v_xor_b32_e32 v161, 0x80000000, v163
	v_xor_b32_e32 v160, 0x80000000, v162
	v_xor_b32_e32 v159, 0x80000000, v191
	v_xor_b32_e32 v158, 0x80000000, v190
	v_pk_mul_f32 v[100:101], v[100:101], v[162:163]
	v_pk_mul_f32 v[98:99], v[98:99], v[190:191]
	ds_write_b128 v124, v[158:161]
	ds_write_b128 v124, v[98:101] offset:512
	ds_write_b128 v124, v[106:109] offset:768
	ds_write_b128 v124, v[110:113] offset:1024
	s_and_saveexec_b64 s[42:43], s[6:7]
	v_lshlrev_b32_e32 v98, 16, v156
	v_and_b32_e32 v99, 0xffff0000, v156
	v_lshlrev_b32_e32 v100, 16, v157
	v_and_b32_e32 v101, 0xffff0000, v157
	ds_write_b128 v186, v[98:101] offset:40960
	s_or_b64 exec, exec, s[42:43]
	v_pk_mul_f32 v[98:99], v[108:109], v[112:113]
	v_pk_mul_f32 v[100:101], v[106:107], v[110:111]
	v_mul_f32_e32 v99, v5, v99
	v_mul_f32_e32 v101, v3, v101
	v_fmac_f32_e32 v101, v2, v100
	v_fmac_f32_e32 v99, v4, v98
	v_add_f32_e32 v98, v101, v99
	v_mov_b32_e32 v100, 0
	s_nop 0
	v_add_f32_dpp v98, v98, v98 row_ror:8 row_mask:0xf bank_mask:0xf bound_ctrl:1
	s_nop 1
	v_add_f32_dpp v98, v98, v98 row_ror:4 row_mask:0xf bank_mask:0xf bound_ctrl:1
	s_nop 1
	v_add_f32_dpp v99, v98, v98 row_ror:2 row_mask:0xf bank_mask:0xf bound_ctrl:1
	s_nop 1
	v_mov_b32_dpp v100, v99 row_ror:1 row_mask:0xf bank_mask:0xf
	s_and_saveexec_b64 s[42:43], s[8:9]
	s_cbranch_execz .LBB0_817
	s_and_b64 vcc, exec, s[4:5]
	s_mov_b64 s[52:53], -1
	s_cbranch_vccnz .LBB0_814
	v_lshl_add_u32 v98, s47, 4, v167
	v_sub_u32_e32 v98, 0x1fbf, v98
	s_mov_b64 s[52:53], 0
